# attention: MLA loop PV/rowsum MFMAs interleaved with exp/cvt + early V reads + early tile staging; diff loop: no vmcnt(0) drain at step top, scalar prefetch of termination position
# speedup vs baseline: 1.0005x; 1.0005x over previous
;     ...
;             if (!wdone && t <= ntw - 1 && t >= 1) { const float pkm = (float)posg[64 * (t - 1) + 63];
;                 const float v = fmaxf(bq0 - m[0], bq1 - m[NM - 1]) + slope2 * pkm; wdone = __all(v < -152.0f) ? 1 : 0; }
.LBB0_168:
	s_add_i32 s20, s26, s48
	s_cmp_eq_u32 s20, 4
	v_readfirstlane_b32 s30, v0
	v_readfirstlane_b32 s20, v0
	s_cbranch_scc1 .LBB0_176
	s_add_i32 s30, s48, 1
	s_cmp_lt_u32 s30, s19
	s_cselect_b64 s[80:81], -1, 0
	s_cmp_ge_u32 s30, s19
	s_cbranch_scc1 .LBB0_173
	v_mov_b32_e32 v205, v3
	v_lshl_add_u64 v[0:1], v[204:205], 1, v[200:201]
	v_mov_b32_e32 v207, v3
	v_lshl_add_u64 v[4:5], v[206:207], 1, v[198:199]
	global_load_dwordx4 v[160:163], v[0:1], off
	global_load_dwordx4 v[164:167], v[4:5], off
	v_readfirstlane_b32 s98, v204
	s_nop 1
	s_lshl_b32 s98, s98, 2
	s_add_u32 s98, s38, s98
	s_addc_u32 s99, s39, 0
	s_load_dword s100, s[98:99], 0xfc
	s_and_saveexec_b64 s[46:47], s[44:45]
	s_cbranch_execz .LBB0_172
	global_load_dword v197, v[202:203], off

;     ...
;             if (!wdone && t <= ntw - 1 && t >= 1) { const float pkm = (float)posg[64 * (t - 1) + 63];
;                 const float v = fmaxf(bq0 - m[0], bq1 - m[NM - 1]) + slope2 * pkm; wdone = __all(v < -152.0f) ? 1 : 0; }
.LBB0_200:
	s_bitcmp1_b32 s30, 0
	s_cselect_b32 s20, 0x4700, 0
	s_addk_i32 s20, 0x100
	v_add3_u32 v0, s20, v209, v210
	s_waitcnt vmcnt(0)
	ds_write_b128 v0, v[164:167]
	s_and_saveexec_b64 s[48:49], s[44:45]
	v_add_u32_e32 v0, s20, v225
	v_cvt_f32_i32_e32 v197, v197
	ds_write_b32 v0, v197 offset:17920
	s_or_b64 exec, exec, s[48:49]
	v_add_u32_e32 v0, s20, v229
	s_movk_i32 s20, 0x2400
	v_add3_u32 v0, v0, v210, s20
	ds_write2_b64 v0, v[160:161], v[162:163] offset1:1
	s_andn2_b64 vcc, exec, s[46:47]
	v_mov_b32_e32 v80, 1
	s_cbranch_vccnz .LBB0_205
.LBB0_203:
	s_cmp_gt_i32 s23, s25
	s_cselect_b64 s[46:47], -1, 0
	s_cmp_lt_i32 s23, 1
	s_cselect_b64 s[48:49], -1, 0
	s_or_b64 s[46:47], s[46:47], s[48:49]
	s_and_b64 vcc, exec, s[46:47]
	v_mov_b32_e32 v80, 0
	s_cbranch_vccnz .LBB0_205
	v_sub_f32_e32 v1, v226, v237
	v_sub_f32_e32 v2, v227, v238
	v_max_f32_e32 v1, v1, v2
	s_mov_b32 s20, 0xc3180000
	s_waitcnt lgkmcnt(0)
	v_cvt_f32_i32_e32 v0, s100
	v_fmac_f32_e32 v1, v211, v0
	v_cmp_gt_f32_e32 vcc, s20, v1
	s_cmp_eq_u64 vcc, exec
	s_cselect_b64 s[46:47], -1, 0
	v_cndmask_b32_e64 v80, 0, 1, s[46:47]

; #define LAS __attribute__((address_space(3)))
; template <bool SUM> __device__ __forceinline__ bool softmax_tile(f32x16& pa, f32x16& pb, float& m, float& l, f32x16& o0, f32x16& o1, bool first) {
;     float rm;
;     if (first) { rm = fmaxf(max16(pa), max16(pb)); rm = fmaxf(rm, __shfl_xor(rm, 32)); }
;     else { int im = max(imax16(pa), imax16(pb));
;         const auto rr = __builtin_amdgcn_permlane32_swap((unsigned)im, (unsigned)im, false, false); im = max((int)rr[0], (int)rr[1]); rm = __int_as_float(im); }
;     bool moved = false;
;     if (first || __any(rm > 8.0f)) {
;         asm volatile("" ::: "memory");
;         const float dl = first ? rm : fmaxf(rm, 0.f); m += dl; moved = true;
;         if (!first) { const float f = __builtin_amdgcn_exp2f(-dl); l *= f;
; #pragma unroll
;             for (int r = 0; r < 16; ++r) { o0[r] *= f; o1[r] *= f; } }
; #pragma unroll
;         for (int r = 0; r < 16; ++r) { pa[r] -= dl; pb[r] -= dl; }
;     }
;     ...
; #pragma unroll
;                     for (int hf = 0; hf < 2; ++hf)
; #pragma unroll
;                         for (int d = 1; d < NQ; ++d) p[hf] = MFMA32(kf[0][hf][d], qr[d], p[hf]);
;                 }
;                 __builtin_amdgcn_sched_barrier(0);
;                 const float l_before = l[mp];
;                 const bool moved = softmax_tile<MODE == 1>(p[0], p[1], m[mp], l[mp], o[mp][0], o[mp][1], first_t);
;                 if constexpr (MODE == 1 && FAST) { if (moved) { unsigned h1, h2, h3; split3_bf16(-m[mp], h1, h2, h3);
;                         if (hi) { const u32x4 qv = {h1 | (h2 << 16), h3, 0u, 0u}; qx[mp] = __builtin_bit_cast(bf16x8, qv); } } }
;                 if (MODE == 0 && moved) { const float f = first_t ? 0.f : l[0] / l_before;
; #pragma unroll
;                     for (int r = 0; r < 16; ++r) { negm[r] = -m[0]; lsum[r] *= f; } l[0] = 1.0f; }
; #pragma unroll
;                 for (int ks = 0; ks < 4; ++ks) pf[mp][ks] = pack_frag(p[ks >> 1], ks & 1);
;             }
;             const LAS unsigned char* vb = bb + KB + r32 * VP + 8 * hi;
; #pragma unroll
;             for (int dh = 0; dh < 2; ++dh) {
;                 bf16x8 vf[4];
; #pragma unroll
;                 for (int ks = 0; ks < 4; ++ks) {
;                     const u32x2 v0 = *(const LAS u32x2*)(vb + dh * 32 * VP + 32 * ks), v1 = *(const LAS u32x2*)(vb + dh * 32 * VP + 32 * ks + 16);
.LBB0_264:
	s_waitcnt lgkmcnt(10)
	v_mfma_f32_32x32x16_bf16 v[68:83], v[172:175], v[108:111], v[68:83]
	s_waitcnt lgkmcnt(4)
	v_mfma_f32_32x32x16_bf16 v[84:99], v[152:155], v[108:111], v[84:99]
	v_mfma_f32_32x32x16_bf16 v[68:83], v[168:171], v[112:115], v[68:83]
	s_waitcnt lgkmcnt(3)
	v_mfma_f32_32x32x16_bf16 v[84:99], v[148:151], v[112:115], v[84:99]
	v_mfma_f32_32x32x16_bf16 v[68:83], v[164:167], v[116:119], v[68:83]
	s_waitcnt lgkmcnt(2)
	v_mfma_f32_32x32x16_bf16 v[84:99], v[144:147], v[116:119], v[84:99]
	v_mfma_f32_32x32x16_bf16 v[68:83], v[160:163], v[124:127], v[68:83]
	s_waitcnt lgkmcnt(1)
	v_mfma_f32_32x32x16_bf16 v[84:99], v[140:143], v[124:127], v[84:99]
	v_mfma_f32_32x32x16_bf16 v[68:83], v[156:159], v[120:123], v[68:83]
	s_waitcnt lgkmcnt(0)
	v_mfma_f32_32x32x16_bf16 v[84:99], v[136:139], v[120:123], v[84:99]
	s_bitcmp1_b32 s12, 0
	s_cselect_b32 s12, 0x5700, 0
	s_addk_i32 s12, 0x100
	v_add3_u32 v180, s12, v200, v201
	s_waitcnt vmcnt(0)
	ds_write_b128 v180, v[132:135]
	s_and_saveexec_b64 s[46:47], s[44:45]
	v_add3_u32 v180, s12, v203, v202
	ds_write_b128 v180, v[100:103] offset:128
	s_or_b64 exec, exec, s[46:47]
	s_mov_b64 s[18:19], 0x1000
	v_add_u32_e32 v180, s12, v210
	v_lshl_add_u64 v[194:195], v[194:195], 0, s[18:19]
	s_mov_b64 s[18:19], 0x10000
	v_add3_u32 v180, v180, v201, s13
	v_lshl_add_u64 v[0:1], v[0:1], 0, s[18:19]
	v_lshl_add_u64 v[196:197], v[196:197], 0, s[8:9]
	ds_write2_b64 v180, v[128:129], v[130:131] offset1:1
	v_add3_u32 v180, s15, v206, v199
	v_add_u32_e32 v181, 0x3000, v180
	v_add_u32_e32 v180, 0x4000, v180
	ds_read2_b64 v[144:147], v181 offset0:128 offset1:130
	ds_read2_b64 v[160:163], v180 offset0:160 offset1:162
	ds_read2_b64 v[148:151], v181 offset0:132 offset1:134
	ds_read2_b64 v[164:167], v180 offset0:164 offset1:166
	ds_read2_b64 v[152:155], v181 offset0:136 offset1:138
	ds_read2_b64 v[168:171], v180 offset0:168 offset1:170
	ds_read2_b64 v[156:159], v181 offset0:140 offset1:142
	ds_read2_b64 v[172:175], v180 offset0:172 offset1:174
	v_max3_i32 v136, v68, v69, v70
	v_max3_i32 v137, v71, v72, v73
	v_max3_i32 v138, v74, v75, v76
	v_max3_i32 v139, v77, v78, v79
	v_max3_i32 v140, v80, v81, v82
	v_max3_i32 v136, v136, v137, v138
	v_max3_i32 v137, v139, v140, v83
	v_max_i32_e32 v138, v84, v85
	v_max3_i32 v139, v87, v88, v89
	v_max3_i32 v141, v93, v94, v95
	v_max3_i32 v142, v96, v97, v98
	v_max3_i32 v140, v90, v91, v92
	v_max3_i32 v138, v138, v86, v139
	v_max3_i32 v139, v141, v142, v99
	v_max3_i32 v138, v138, v140, v139
	v_max3_i32 v136, v136, v137, v138
	v_mov_b32_e32 v137, v136
	s_nop 1
	v_permlane32_swap_b32_e32 v136, v137
	v_max_i32_e32 v136, v136, v137
	v_cmp_lt_f32_e32 vcc, s17, v136
	s_cmp_lg_u64 vcc, 0
	s_cselect_b64 s[46:47], -1, 0
	s_cbranch_vccz .LBB0_272
	v_max_f32_e32 v136, v136, v136
	v_max_f32_e32 v138, 0, v136
	v_exp_f32_e64 v140, -v138
	v_add_f32_e32 v207, v207, v138
	v_pk_add_f32 v[68:69], v[68:69], v[138:139] op_sel_hi:[1,0] neg_lo:[0,1] neg_hi:[0,1]
	v_mul_f32_e32 v136, v208, v140
	v_pk_mul_f32 v[34:35], v[34:35], v[140:141] op_sel_hi:[1,0]
	v_pk_mul_f32 v[32:33], v[32:33], v[140:141] op_sel_hi:[1,0]
	v_pk_mul_f32 v[30:31], v[30:31], v[140:141] op_sel_hi:[1,0]
	v_pk_mul_f32 v[28:29], v[28:29], v[140:141] op_sel_hi:[1,0]
	v_pk_mul_f32 v[26:27], v[26:27], v[140:141] op_sel_hi:[1,0]
	v_pk_mul_f32 v[24:25], v[24:25], v[140:141] op_sel_hi:[1,0]
	v_pk_mul_f32 v[22:23], v[22:23], v[140:141] op_sel_hi:[1,0]
	v_pk_mul_f32 v[20:21], v[20:21], v[140:141] op_sel_hi:[1,0]
	v_pk_mul_f32 v[18:19], v[18:19], v[140:141] op_sel_hi:[1,0]
	v_pk_mul_f32 v[16:17], v[16:17], v[140:141] op_sel_hi:[1,0]
	v_pk_mul_f32 v[14:15], v[14:15], v[140:141] op_sel_hi:[1,0]
	v_pk_mul_f32 v[12:13], v[12:13], v[140:141] op_sel_hi:[1,0]
	v_pk_mul_f32 v[10:11], v[10:11], v[140:141] op_sel_hi:[1,0]
	v_pk_mul_f32 v[8:9], v[8:9], v[140:141] op_sel_hi:[1,0]
	v_pk_mul_f32 v[6:7], v[6:7], v[140:141] op_sel_hi:[1,0]
	v_pk_mul_f32 v[4:5], v[4:5], v[140:141] op_sel_hi:[1,0]
	v_pk_add_f32 v[84:85], v[84:85], v[138:139] op_sel_hi:[1,0] neg_lo:[0,1] neg_hi:[0,1]
	v_pk_add_f32 v[70:71], v[70:71], v[138:139] op_sel_hi:[1,0] neg_lo:[0,1] neg_hi:[0,1]
	v_pk_add_f32 v[86:87], v[86:87], v[138:139] op_sel_hi:[1,0] neg_lo:[0,1] neg_hi:[0,1]
	v_pk_add_f32 v[72:73], v[72:73], v[138:139] op_sel_hi:[1,0] neg_lo:[0,1] neg_hi:[0,1]
	v_pk_add_f32 v[88:89], v[88:89], v[138:139] op_sel_hi:[1,0] neg_lo:[0,1] neg_hi:[0,1]
	v_pk_add_f32 v[74:75], v[74:75], v[138:139] op_sel_hi:[1,0] neg_lo:[0,1] neg_hi:[0,1]
	v_pk_add_f32 v[90:91], v[90:91], v[138:139] op_sel_hi:[1,0] neg_lo:[0,1] neg_hi:[0,1]
	v_pk_add_f32 v[76:77], v[76:77], v[138:139] op_sel_hi:[1,0] neg_lo:[0,1] neg_hi:[0,1]
	v_pk_add_f32 v[92:93], v[92:93], v[138:139] op_sel_hi:[1,0] neg_lo:[0,1] neg_hi:[0,1]
	v_pk_add_f32 v[78:79], v[78:79], v[138:139] op_sel_hi:[1,0] neg_lo:[0,1] neg_hi:[0,1]
	v_pk_add_f32 v[94:95], v[94:95], v[138:139] op_sel_hi:[1,0] neg_lo:[0,1] neg_hi:[0,1]
	v_pk_add_f32 v[80:81], v[80:81], v[138:139] op_sel_hi:[1,0] neg_lo:[0,1] neg_hi:[0,1]
	v_pk_add_f32 v[96:97], v[96:97], v[138:139] op_sel_hi:[1,0] neg_lo:[0,1] neg_hi:[0,1]
	v_pk_add_f32 v[82:83], v[82:83], v[138:139] op_sel_hi:[1,0] neg_lo:[0,1] neg_hi:[0,1]
	v_pk_add_f32 v[98:99], v[98:99], v[138:139] op_sel_hi:[1,0] neg_lo:[0,1] neg_hi:[0,1]
	s_andn2_b64 vcc, exec, s[46:47]
	s_cbranch_vccnz .LBB0_267

; #define LAS __attribute__((address_space(3)))
; #define MFMA32(a, b, c) __builtin_amdgcn_mfma_f32_32x32x16_bf16((a), (b), (c), 0, 0, 0)
; template <bool SUM> __device__ __forceinline__ bool softmax_tile(f32x16& pa, f32x16& pb, float& m, float& l, f32x16& o0, f32x16& o1, bool first) {
;     ...
; #pragma unroll
;     for (int r = 0; r < 16; ++r) { pa[r] = __builtin_amdgcn_exp2f(pa[r]); pb[r] = __builtin_amdgcn_exp2f(pb[r]); }
;     ...
;                 for (int ks = 0; ks < 4; ++ks) pf[mp][ks] = pack_frag(p[ks >> 1], ks & 1);
;             }
;             const LAS unsigned char* vb = bb + KB + r32 * VP + 8 * hi;
; #pragma unroll
;             for (int dh = 0; dh < 2; ++dh) {
;                 bf16x8 vf[4];
; #pragma unroll
;                 for (int ks = 0; ks < 4; ++ks) {
;                     const u32x2 v0 = *(const LAS u32x2*)(vb + dh * 32 * VP + 32 * ks), v1 = *(const LAS u32x2*)(vb + dh * 32 * VP + 32 * ks + 16);
;                     const u32x4 vv = {v0.x, v0.y, v1.x, v1.y}; vf[ks] = __builtin_bit_cast(bf16x8, vv); }
;                 __builtin_amdgcn_sched_barrier(0);
; #pragma unroll
;                 for (int ks = 0; ks < 4; ++ks)
; #pragma unroll
;                     for (int mp = 0; mp < NM; ++mp) o[mp][dh] = MFMA32(vf[ks], pf[mp][ks], o[mp][dh]);
;                 __builtin_amdgcn_sched_barrier(0);
;             }
;             if constexpr (MODE == 0) {
;                 const u32x4 o1 = {0x3f803f80u, 0x3f803f80u, 0x3f803f80u, 0x3f803f80u}; const bf16x8 ones = __builtin_bit_cast(bf16x8, o1);
; #pragma unroll
;                 for (int ks = 0; ks < 4; ++ks) lsum = MFMA32(ones, pf[0][ks], lsum);
.LBB0_267:
	v_exp_f32_e32 v68, v68
	v_exp_f32_e32 v69, v69
	v_exp_f32_e32 v70, v70
	v_exp_f32_e32 v71, v71
	v_exp_f32_e32 v72, v72
	v_exp_f32_e32 v73, v73
	v_exp_f32_e32 v74, v74
	v_exp_f32_e32 v75, v75
	v_cvt_pk_bf16_f32 v68, v68, v69
	v_cvt_pk_bf16_f32 v69, v70, v71
	v_cvt_pk_bf16_f32 v70, v72, v73
	v_cvt_pk_bf16_f32 v71, v74, v75
	s_mov_b32 s70, s68
	s_mov_b32 s71, s68
	s_mov_b32 s69, s68
	v_mov_b64_e32 v[178:179], s[70:71]
	v_mov_b64_e32 v[176:177], s[68:69]
	v_mov_b32_e32 v208, v136
	s_waitcnt lgkmcnt(6)
	v_mfma_f32_32x32x16_bf16 v[4:19], v[144:147], v[68:71], v[4:19]
	v_exp_f32_e32 v76, v76
	v_exp_f32_e32 v77, v77
	v_exp_f32_e32 v78, v78
	v_mfma_f32_32x32x16_bf16 v[20:35], v[160:163], v[68:71], v[20:35]
	v_exp_f32_e32 v79, v79
	v_exp_f32_e32 v80, v80
	v_exp_f32_e32 v81, v81
	v_mfma_f32_32x32x16_bf16 v[36:51], v[176:179], v[68:71], v[36:51]
	v_exp_f32_e32 v82, v82
	v_exp_f32_e32 v83, v83
	v_cvt_pk_bf16_f32 v72, v76, v77
	v_cvt_pk_bf16_f32 v73, v78, v79
	v_cvt_pk_bf16_f32 v74, v80, v81
	v_cvt_pk_bf16_f32 v75, v82, v83
	s_waitcnt lgkmcnt(4)
	s_nop 0
	v_mfma_f32_32x32x16_bf16 v[4:19], v[148:151], v[72:75], v[4:19]
	v_exp_f32_e32 v84, v84
	v_exp_f32_e32 v85, v85
	v_exp_f32_e32 v86, v86
	v_mfma_f32_32x32x16_bf16 v[20:35], v[164:167], v[72:75], v[20:35]
	v_exp_f32_e32 v87, v87
	v_exp_f32_e32 v88, v88
	v_exp_f32_e32 v89, v89
	v_mfma_f32_32x32x16_bf16 v[36:51], v[176:179], v[72:75], v[36:51]
	v_exp_f32_e32 v90, v90
	v_exp_f32_e32 v91, v91
	v_cvt_pk_bf16_f32 v76, v84, v85
	v_cvt_pk_bf16_f32 v77, v86, v87
	v_cvt_pk_bf16_f32 v78, v88, v89
	v_cvt_pk_bf16_f32 v79, v90, v91
	s_waitcnt lgkmcnt(2)
	s_nop 0
	v_mfma_f32_32x32x16_bf16 v[4:19], v[152:155], v[76:79], v[4:19]
	v_exp_f32_e32 v92, v92
	v_exp_f32_e32 v93, v93
	v_exp_f32_e32 v94, v94
	v_mfma_f32_32x32x16_bf16 v[20:35], v[168:171], v[76:79], v[20:35]
	v_exp_f32_e32 v95, v95
	v_exp_f32_e32 v96, v96
	v_exp_f32_e32 v97, v97
	v_mfma_f32_32x32x16_bf16 v[36:51], v[176:179], v[76:79], v[36:51]
	v_exp_f32_e32 v98, v98
	v_exp_f32_e32 v99, v99
	v_cvt_pk_bf16_f32 v80, v92, v93
	v_cvt_pk_bf16_f32 v81, v94, v95
	v_cvt_pk_bf16_f32 v82, v96, v97
	v_cvt_pk_bf16_f32 v83, v98, v99
	s_waitcnt lgkmcnt(0)
	s_nop 0
	v_mfma_f32_32x32x16_bf16 v[4:19], v[156:159], v[80:83], v[4:19]
	v_mfma_f32_32x32x16_bf16 v[20:35], v[172:175], v[80:83], v[20:35]
	v_mfma_f32_32x32x16_bf16 v[36:51], v[176:179], v[80:83], v[36:51]
	s_cmp_lg_u32 s5, s11
	s_branch .Lmla_join

;     ...
;         if (it + 1 < NT) ATT_STORE((it + 1) & 1);
;         if constexpr (REV) {
;             if (!wdone && t <= ntw - 1 && t >= 1) { const float pkm = (float)posg[64 * (t - 1) + 63];
;                 const float v = fmaxf(bq0 - m[0], bq1 - m[NM - 1]) + slope2 * pkm; wdone = __all(v < -152.0f) ? 1 : 0; }
;             if (__syncthreads_and(wdone)) break;
;         } else __syncthreads();
.Lmla_join:
	s_waitcnt lgkmcnt(0)
	s_barrier
	s_cbranch_scc0 .LBB0_273
	s_mov_b32 s12, s11
	global_load_dwordx4 v[128:131], v[196:197], off
	global_load_dwordx4 v[132:135], v[0:1], off
	s_and_saveexec_b64 s[46:47], s[44:45]
	s_cbranch_execnz .LBB0_258
	s_branch .LBB0_259
